# attention: static s_setprio 1 for waves 4-7; P12 output stores nt
# baseline (speedup 1.0000x reference)
.LBB0_729:
	s_waitcnt lgkmcnt(0)
	v_and_b32_e32 v1, 31, v145
	v_readlane_b32 s0, v244, 25
	v_lshrrev_b32_e32 v6, 3, v145
	v_mov_b64_e32 v[2:3], s[54:55]
	v_lshl_or_b32 v137, s0, 5, v1
	s_cmp_ge_u32 s0, 4
	s_cbranch_scc0 .Lattn_prio_done
	s_setprio 1
.Lattn_prio_done:
	s_movk_i32 s0, 0x100
	v_cmp_gt_u32_e64 s[2:3], s0, v145
	s_movk_i32 s0, 0x2200
	v_mad_u64_u32 v[2:3], s[0:1], v6, s0, v[2:3]
	v_bfe_u32 v8, v145, 2, 6
	s_movk_i32 s0, 0xd0
	s_add_u32 s22, s54, 0x2400000
	v_mad_u32_u24 v143, v6, s0, 0
	v_mul_u32_u24_e32 v174, 0xd0, v8
	v_mad_u32_u24 v8, v8, s0, 0
	s_movk_i32 s0, 0xffb8
	s_addc_u32 s23, s55, 0
	v_mov_b32_e32 v97, 0
	v_and_b32_e32 v4, 7, v145
	v_mad_i32_i24 v177, v6, s0, v143
	s_movk_i32 s1, 0x48
	v_lshrrev_b32_e32 v5, 5, v144
	s_add_u32 s37, s54, 0x1ab00000
	v_and_b32_e32 v9, 3, v145
	v_lshlrev_b32_e32 v148, 4, v4
	v_mad_u32_u24 v178, v6, s1, v177
	v_mov_b32_e32 v149, v97
	s_addc_u32 s38, s55, 0
	v_lshlrev_b32_e32 v138, 7, v6
	v_lshlrev_b32_e32 v0, 3, v4
	v_lshlrev_b32_e32 v142, 3, v9
	v_mul_hi_u32_u24_e32 v147, 0x2200, v6
	v_mul_u32_u24_e32 v10, 0x2200, v6
	v_mul_u32_u24_e32 v141, 0xd0, v6
	v_lshlrev_b32_e32 v175, 4, v9
	v_mul_u32_u24_e32 v176, 0x88, v6
	v_lshlrev_b32_e32 v4, 6, v6
	v_mad_i32_i24 v9, v6, s0, v178
	v_lshlrev_b32_e32 v179, 4, v5
	v_or_b32_e32 v6, 32, v144
	v_lshl_add_u64 v[2:3], v[2:3], 0, v[148:149]
	s_mov_b64 s[0:1], 0x1cd00000
	v_lshlrev_b32_e32 v136, 3, v5
	s_add_u32 s39, s54, 0x1ef00000
	v_lshrrev_b32_e32 v7, 2, v145
	v_add_u32_e32 v11, 0, v179
	v_mul_u32_u24_e32 v180, 0xd0, v1
	v_mul_u32_u24_e32 v181, 0xd0, v6
	v_mul_u32_u24_e32 v183, 0x88, v6
	v_lshlrev_b32_e32 v6, 2, v5
	v_lshl_add_u64 v[150:151], v[2:3], 0, s[0:1]
	v_lshlrev_b32_e32 v156, 1, v0
	s_mov_b32 s0, 0x8a00
	v_mbcnt_lo_u32_b32 v0, -1, 0
	s_addc_u32 s40, s55, 0
	v_mov_b32_e32 v139, v97
	v_lshlrev_b32_e32 v140, 5, v7
	s_mov_b32 s25, 0
	v_mul_u32_u24_e32 v182, 0x88, v1
	v_lshl_or_b32 v152, v7, 6, v175
	v_mov_b32_e32 v153, v97
	v_or_b32_e32 v146, v10, v148
	v_or_b32_e32 v154, v138, v148
	v_mov_b32_e32 v155, v97
	s_movk_i32 s41, 0x3400
	v_lshlrev_b32_e32 v158, 1, v4
	v_add3_u32 v149, v9, v148, s0
	v_add_u32_e32 v185, v11, v180
	s_mov_b32 s42, 0x41000000
	s_mov_b64 s[26:27], 0x2000
	s_mov_b64 s[28:29], 0x100
	s_mov_b64 s[30:31], 0x4000
	v_lshlrev_b32_e32 v160, 1, v6
	v_lshlrev_b32_e32 v162, 1, v136
	v_mov_b32_e32 v163, v97
	v_mov_b32_e32 v164, v156
	v_mov_b32_e32 v165, v97
	v_add_u32_e32 v186, v8, v175
	v_mbcnt_hi_u32_b32 v187, -1, v0
	s_branch .LBB0_731

.LBB0_762:
	s_setprio 0
	s_cmp_gt_i32 s57, 5
	s_cselect_b64 s[0:1], -1, 0
	s_and_b64 s[2:3], s[20:21], s[0:1]
	s_andn2_b64 vcc, exec, s[2:3]
	s_cbranch_vccnz .LBB0_816
	s_waitcnt vmcnt(0)
	s_waitcnt vmcnt(0) lgkmcnt(0)
	s_barrier
	s_mov_b64 s[2:3], exec
	v_readlane_b32 s4, v244, 2
	v_readlane_b32 s5, v244, 3
	s_and_b64 s[4:5], s[2:3], s[4:5]
	s_mov_b64 exec, s[4:5]
	s_cbranch_execz .LBB0_815
	s_add_i32 s4, 0, 0x23fc0
	v_mov_b32_e32 v0, s4
	s_waitcnt vmcnt(0) expcnt(0) lgkmcnt(0)
	ds_read_b32 v2, v0
	s_add_i32 s4, 0, 0x23fc4
	v_mov_b32_e32 v0, s4
	ds_read_b32 v0, v0
	s_waitcnt lgkmcnt(1)
	v_cmp_ne_u32_e32 vcc, 0, v2
	s_cbranch_vccnz .LBB0_779
	v_readlane_b32 s4, v244, 0
	s_mul_i32 s44, s73, s4
	s_add_u32 s4, s54, 0x68200
	s_addc_u32 s5, s55, 0
	s_add_u32 s6, s54, 0x68400
	s_addc_u32 s7, s55, 0
	s_add_u32 s8, s54, 0x68500
	s_addc_u32 s9, s55, 0
	s_add_u32 s10, s54, 0x68600
	s_addc_u32 s11, s55, 0
	s_add_u32 s12, s54, 0x68700
	s_addc_u32 s13, s55, 0
	s_add_u32 s14, s54, 0x68800
	s_addc_u32 s15, s55, 0
	s_add_u32 s16, s54, 0x68900
	s_addc_u32 s17, s55, 0
	s_add_u32 s18, s54, 0x68a00
	s_addc_u32 s19, s55, 0
	s_add_u32 s20, s54, 0x68b00
	s_addc_u32 s21, s55, 0
	s_add_u32 s22, s54, 0x68c00
	s_addc_u32 s23, s55, 0
	s_add_u32 s24, s54, 0x68d00
	s_addc_u32 s25, s55, 0
	s_add_u32 s26, s54, 0x68e00
	s_addc_u32 s27, s55, 0
	s_add_u32 s28, s54, 0x68f00
	s_addc_u32 s29, s55, 0
	s_add_u32 s30, s54, 0x69000
	s_addc_u32 s31, s55, 0
	s_add_u32 s34, s54, 0x69100
	s_addc_u32 s35, s55, 0
	s_add_u32 s36, s54, 0x69200
	s_addc_u32 s37, s55, 0
	s_add_u32 s38, s54, 0x69300
	s_mul_i32 s44, s44, s72
	s_addc_u32 s39, s55, 0
	s_mov_b32 s45, 1
	v_mov_b32_e32 v16, 0
	s_branch .LBB0_767

.Lp12_nonext:
	v_mul_f32_e32 v80, v48, v48
	v_mul_f32_e32 v82, v64, v64
	v_mul_f32_e32 v81, v49, v49
	v_mul_f32_e32 v83, v65, v65
	v_fmac_f32_e32 v80, v50, v50
	v_fmac_f32_e32 v82, v66, v66
	v_fmac_f32_e32 v81, v51, v51
	v_fmac_f32_e32 v83, v67, v67
	v_fmac_f32_e32 v80, v52, v52
	v_fmac_f32_e32 v82, v68, v68
	v_fmac_f32_e32 v81, v53, v53
	v_fmac_f32_e32 v83, v69, v69
	v_fmac_f32_e32 v80, v54, v54
	v_fmac_f32_e32 v82, v70, v70
	v_fmac_f32_e32 v81, v55, v55
	v_fmac_f32_e32 v83, v71, v71
	v_fmac_f32_e32 v80, v56, v56
	v_fmac_f32_e32 v82, v72, v72
	v_fmac_f32_e32 v81, v57, v57
	v_fmac_f32_e32 v83, v73, v73
	v_fmac_f32_e32 v80, v58, v58
	v_fmac_f32_e32 v82, v74, v74
	v_fmac_f32_e32 v81, v59, v59
	v_fmac_f32_e32 v83, v75, v75
	v_fmac_f32_e32 v80, v60, v60
	v_fmac_f32_e32 v82, v76, v76
	v_fmac_f32_e32 v81, v61, v61
	v_fmac_f32_e32 v83, v77, v77
	v_fmac_f32_e32 v80, v62, v62
	v_fmac_f32_e32 v82, v78, v78
	v_fmac_f32_e32 v81, v63, v63
	v_fmac_f32_e32 v83, v79, v79
	v_add_f32_e32 v80, v80, v81
	v_add_f32_e32 v82, v82, v83
	ds_bpermute_b32 v84, v40, v80
	ds_bpermute_b32 v85, v40, v82
	s_waitcnt lgkmcnt(1)
	v_add_f32_e32 v80, v80, v84
	s_waitcnt lgkmcnt(0)
	v_add_f32_e32 v82, v82, v85
	ds_bpermute_b32 v84, v41, v80
	ds_bpermute_b32 v85, v41, v82
	s_waitcnt lgkmcnt(1)
	v_add_f32_e32 v80, v80, v84
	s_waitcnt lgkmcnt(0)
	v_add_f32_e32 v82, v82, v85
	ds_bpermute_b32 v84, v42, v80
	ds_bpermute_b32 v85, v42, v82
	s_waitcnt lgkmcnt(1)
	v_add_f32_e32 v80, v80, v84
	s_waitcnt lgkmcnt(0)
	v_add_f32_e32 v82, v82, v85
	ds_bpermute_b32 v84, v43, v80
	ds_bpermute_b32 v85, v43, v82
	s_waitcnt lgkmcnt(1)
	v_add_f32_e32 v80, v80, v84
	s_waitcnt lgkmcnt(0)
	v_add_f32_e32 v82, v82, v85
	ds_bpermute_b32 v84, v44, v80
	ds_bpermute_b32 v85, v44, v82
	s_waitcnt lgkmcnt(1)
	v_add_f32_e32 v80, v80, v84
	s_waitcnt lgkmcnt(0)
	v_add_f32_e32 v82, v82, v85
	ds_bpermute_b32 v84, v45, v80
	ds_bpermute_b32 v85, v45, v82
	s_waitcnt lgkmcnt(1)
	v_add_f32_e32 v80, v80, v84
	s_waitcnt lgkmcnt(0)
	v_add_f32_e32 v82, v82, v85
	v_fmamk_f32 v80, v80, 0x3a800000, v86
	v_fmamk_f32 v82, v82, 0x3a800000, v86
	v_rsq_f32_e32 v80, v80
	v_rsq_f32_e32 v82, v82
	s_nop 0
	v_mul_f32_e32 v48, v48, v80
	v_mul_f32_e32 v64, v64, v82
	v_mul_f32_e32 v49, v49, v80
	v_mul_f32_e32 v65, v65, v82
	v_mul_f32_e32 v50, v50, v80
	v_mul_f32_e32 v66, v66, v82
	v_mul_f32_e32 v51, v51, v80
	v_mul_f32_e32 v67, v67, v82
	v_mul_f32_e32 v52, v52, v80
	v_mul_f32_e32 v68, v68, v82
	v_mul_f32_e32 v53, v53, v80
	v_mul_f32_e32 v69, v69, v82
	v_mul_f32_e32 v54, v54, v80
	v_mul_f32_e32 v70, v70, v82
	v_mul_f32_e32 v55, v55, v80
	v_mul_f32_e32 v71, v71, v82
	v_mul_f32_e32 v56, v56, v80
	v_mul_f32_e32 v72, v72, v82
	v_mul_f32_e32 v57, v57, v80
	v_mul_f32_e32 v73, v73, v82
	v_mul_f32_e32 v58, v58, v80
	v_mul_f32_e32 v74, v74, v82
	v_mul_f32_e32 v59, v59, v80
	v_mul_f32_e32 v75, v75, v82
	v_mul_f32_e32 v60, v60, v80
	v_mul_f32_e32 v76, v76, v82
	v_mul_f32_e32 v61, v61, v80
	v_mul_f32_e32 v77, v77, v82
	v_mul_f32_e32 v62, v62, v80
	v_mul_f32_e32 v78, v78, v82
	v_mul_f32_e32 v63, v63, v80
	v_mul_f32_e32 v79, v79, v82
	v_mul_f32_e32 v48, v48, v100
	v_mul_f32_e32 v64, v64, v100
	v_mul_f32_e32 v49, v49, v101
	v_mul_f32_e32 v65, v65, v101
	v_mul_f32_e32 v50, v50, v102
	v_mul_f32_e32 v66, v66, v102
	v_mul_f32_e32 v51, v51, v103
	v_mul_f32_e32 v67, v67, v103
	v_mul_f32_e32 v52, v52, v104
	v_mul_f32_e32 v68, v68, v104
	v_mul_f32_e32 v53, v53, v105
	v_mul_f32_e32 v69, v69, v105
	v_mul_f32_e32 v54, v54, v106
	v_mul_f32_e32 v70, v70, v106
	v_mul_f32_e32 v55, v55, v107
	v_mul_f32_e32 v71, v71, v107
	v_mul_f32_e32 v56, v56, v108
	v_mul_f32_e32 v72, v72, v108
	v_mul_f32_e32 v57, v57, v109
	v_mul_f32_e32 v73, v73, v109
	v_mul_f32_e32 v58, v58, v110
	v_mul_f32_e32 v74, v74, v110
	v_mul_f32_e32 v59, v59, v111
	v_mul_f32_e32 v75, v75, v111
	v_mul_f32_e32 v60, v60, v112
	v_mul_f32_e32 v76, v76, v112
	v_mul_f32_e32 v61, v61, v113
	v_mul_f32_e32 v77, v77, v113
	v_mul_f32_e32 v62, v62, v114
	v_mul_f32_e32 v78, v78, v114
	v_mul_f32_e32 v63, v63, v115
	v_mul_f32_e32 v79, v79, v115
	global_store_dwordx4 v2, v[48:51], s[14:15] nt
	global_store_dwordx4 v2, v[52:55], s[14:15] offset:1024 nt
	global_store_dwordx4 v2, v[56:59], s[14:15] offset:2048 nt
	global_store_dwordx4 v2, v[60:63], s[14:15] offset:3072 nt
	global_store_dwordx4 v2, v[64:67], s[16:17] nt
	global_store_dwordx4 v2, v[68:71], s[16:17] offset:1024 nt
	global_store_dwordx4 v2, v[72:75], s[16:17] offset:2048 nt
	global_store_dwordx4 v2, v[76:79], s[16:17] offset:3072 nt
	s_cmp_lg_u32 s18, 0
	s_cbranch_scc0 .LBB0_1347
	s_waitcnt vmcnt(8)
	s_branch .Lp12_loop
